# fp8 weight conversion in MIX: scale word by SMEM load and counted vmcnt on the prefetch path (hipcc's vmcnt(0) drained the prefetched item twice per item)
# speedup vs baseline: 1.0053x; 1.0053x over previous
; __device__ __forceinline__ float w_qscale(float wmax) { return exp2f(floorf(log2f(128.f / fmaxf(wmax, 1e-30f)))); }
; __device__ __forceinline__ bool witem_decode(const Frame& F, int l, int it, WItem& t) {
;     constexpr int I_GU = 4 * 16, I_DN = 4 * 8, N_GU = NE * I_GU, N_DN = NE * I_DN;
;     const float* wmax = (const float*)((const unsigned*)(F.ws + WS_CTL) + CW_WMAX);
;     int r = it, nblk, item;
;     if (r < N_GU) { const int le = l * NE + r / I_GU; t.W = F.in[16] + (size_t)le * D * 2048; t.WT = (unsigned char*)(F.ws + WS_WGU) + (size_t)le * 2048 * D; t.N = 2048; t.map = 1; nblk = 16; item = r % I_GU; t.scale = w_qscale(wmax[l * 2 + 0]); }
;     else if ((r -= N_GU) < N_DN) { const int le = l * NE + r / I_DN; t.W = F.in[18] + (size_t)le * FF * D; t.WT = (unsigned char*)(F.ws + WS_WDN) + (size_t)le * D * FF; t.N = D; t.map = 3; nblk = 8; item = r % I_DN; t.scale = w_qscale(wmax[l * 2 + 1]); }
;     else return false;
;     t.k0 = 256 * (item / nblk); t.n0 = 128 * (item % nblk); return true;
; }
; __device__ __forceinline__ void witem_load(const WItem& t, int wave, int lane, f32x4 (&v)[16]) {
;     const float* wp = t.W + (size_t)(t.k0 + 32 * wave + 16 * (lane >> 5)) * t.N + t.n0 + 4 * (lane & 31);
; #pragma unroll
;     for (int q = 0; q < 16; ++q) v[q] = __builtin_nontemporal_load((const f32x4*)(wp + (size_t)q * t.N));
; }
; __device__ __forceinline__ void fp8_convert_range(const Frame& F, int l, int start, int stride, int limit) {
;     ...
;     WItem ta, tb; f32x4 va[16], vb[16];
;     int it = start;
;     bool ha = it < limit && witem_decode(F, l, it, ta);
;     if (ha) witem_load(ta, F.wave, F.lane, va);
;     while (ha) {
;         const bool hb = it + stride < limit && witem_decode(F, l, it + stride, tb);
;         if (hb) witem_load(tb, F.wave, F.lane, vb);
.LBB0_1427:
	s_load_dword s100, s[4:5], 0x0
	s_mov_b32 s7, 0x43000000
	v_lshlrev_b32_e32 v198, 2, v136
	s_waitcnt lgkmcnt(0)
	v_mov_b32_e32 v6, s100
	v_max_f32_e32 v6, v6, v6
	v_max_f32_e32 v6, 0xda24260, v6
	v_div_scale_f32 v7, s[4:5], v6, v6, s7
	v_rcp_f32_e32 v8, v7
	s_mov_b32 s4, 0x800000
	v_fma_f32 v9, -v7, v8, 1.0
	v_fmac_f32_e32 v8, v9, v8
	v_div_scale_f32 v9, vcc, s7, v6, s7
	v_mul_f32_e32 v70, v9, v8
	v_fma_f32 v71, -v7, v70, v9
	v_fmac_f32_e32 v70, v71, v8
	v_fma_f32 v7, -v7, v70, v9
	v_div_fmas_f32 v7, v7, v8, v70
	v_div_fixup_f32 v6, v7, v6, s7
	v_cmp_gt_f32_e32 vcc, s4, v6
	s_and_b64 s[4:5], vcc, exec
	s_cselect_b32 s4, 32, 0
	v_ldexp_f32 v6, v6, s4
	v_log_f32_e32 v6, v6
	v_cndmask_b32_e32 v7, 0, v232, vcc
	s_mov_b32 s4, 0xc2fc0000
	v_sub_f32_e32 v6, v6, v7
	v_floor_f32_e32 v6, v6
	v_cmp_gt_f32_e32 vcc, s4, v6
	s_and_b64 s[4:5], vcc, exec
	s_cselect_b32 s4, 0xffffffc0, 0
	v_cndmask_b32_e32 v7, 0, v233, vcc
	v_add_f32_e32 v6, v6, v7
	v_exp_f32_e32 v6, v6
	v_cvt_f32_ubyte0_e32 v7, s6
	v_rcp_iflag_f32_e32 v8, v7
	v_ldexp_f32 v149, v6, s4
	s_sext_i32_i8 s4, s3
	v_cvt_f32_i32_e32 v6, s4
	s_ashr_i32 s5, s4, 30
	s_or_b32 s7, s5, 1
	v_mul_f32_e32 v8, v6, v8
	v_trunc_f32_e32 v8, v8
	v_fma_f32 v6, -v8, v7, v6
	v_cvt_i32_f32_e32 v8, v8
	v_cmp_ge_f32_e64 s[4:5], |v6|, v7
	s_and_b64 s[4:5], s[4:5], exec
	s_cselect_b32 s4, s7, 0
	v_readfirstlane_b32 s5, v8
	s_add_i32 s4, s5, s4
	s_sext_i32_i8 s5, s4
	s_mul_i32 s4, s4, s6
	s_lshl_b32 s44, s5, 8
	s_sub_i32 s3, s3, s4
	s_sext_i32_i8 s3, s3
	v_add_u32_e32 v6, s44, v143
	s_lshl_b32 s46, s3, 7
	v_mad_i64_i32 v[6:7], s[4:5], s26, v6, 0
	v_lshl_add_u64 v[6:7], v[6:7], 2, s[50:51]
	s_ashr_i32 s47, s46, 31
	v_lshl_add_u64 v[6:7], s[46:47], 2, v[6:7]
	v_lshl_add_u64 v[70:71], v[6:7], 0, v[198:199]
	s_lshl_b32 s34, s26, 2
	v_lshl_add_u64 v[74:75], v[70:71], 0, s[34:35]
	v_lshl_add_u64 v[78:79], v[74:75], 0, s[34:35]
	v_lshl_add_u64 v[82:83], v[78:79], 0, s[34:35]
	v_lshl_add_u64 v[86:87], v[82:83], 0, s[34:35]
	v_lshl_add_u64 v[90:91], v[86:87], 0, s[34:35]
	v_lshl_add_u64 v[94:95], v[90:91], 0, s[34:35]
	v_lshl_add_u64 v[98:99], v[94:95], 0, s[34:35]
	v_lshl_add_u64 v[102:103], v[98:99], 0, s[34:35]
	v_lshl_add_u64 v[106:107], v[102:103], 0, s[34:35]
	v_lshl_add_u64 v[110:111], v[106:107], 0, s[34:35]
	v_lshl_add_u64 v[114:115], v[110:111], 0, s[34:35]
	v_lshl_add_u64 v[118:119], v[114:115], 0, s[34:35]
	v_lshl_add_u64 v[122:123], v[118:119], 0, s[34:35]
	v_lshl_add_u64 v[126:127], v[122:123], 0, s[34:35]
	global_load_dwordx4 v[6:9], v[70:71], off nt
	s_nop 0
	global_load_dwordx4 v[70:73], v[74:75], off nt
	s_nop 0
	global_load_dwordx4 v[74:77], v[78:79], off nt
	s_nop 0
	global_load_dwordx4 v[78:81], v[82:83], off nt
	s_nop 0
	global_load_dwordx4 v[82:85], v[86:87], off nt
	s_nop 0
	global_load_dwordx4 v[86:89], v[90:91], off nt
	s_nop 0
	global_load_dwordx4 v[90:93], v[94:95], off nt
	s_nop 0
	global_load_dwordx4 v[94:97], v[98:99], off nt
	s_nop 0
	global_load_dwordx4 v[98:101], v[102:103], off nt
	s_nop 0
	global_load_dwordx4 v[102:105], v[106:107], off nt
	s_nop 0
	global_load_dwordx4 v[106:109], v[110:111], off nt
	s_nop 0
	global_load_dwordx4 v[110:113], v[114:115], off nt
	s_nop 0
	global_load_dwordx4 v[114:117], v[118:119], off nt
	s_nop 0
	global_load_dwordx4 v[118:121], v[122:123], off nt
	s_nop 0
	global_load_dwordx4 v[122:125], v[126:127], off nt
	v_lshl_add_u64 v[126:127], v[126:127], 0, s[34:35]
	global_load_dwordx4 v[126:129], v[126:127], off nt
	s_waitcnt vmcnt(16)
	v_mul_f32_e32 v131, v2, v1
	s_branch .Lcvw_0

; #define LAS __attribute__((address_space(3)))
; __device__ __forceinline__ int map_row_rt(int map, int n) { return map == 0 ? n : (map == 1 ? map_row<1>(n) : (map == 3 ? map_row<3>(n) : map_row<2>(n))); }
; __device__ __forceinline__ void witem_store(const Frame& F, const WItem& t, const f32x4 (&v)[16], LAS unsigned char* tile) {
;     const int i = F.lane & 31, hi = F.lane >> 5;
; #pragma unroll
;     for (int j = 0; j < 4; ++j) {
;         u32x4 o;
; #pragma unroll
;         for (int d = 0; d < 4; ++d) { int r = __builtin_amdgcn_cvt_pk_fp8_f32(v[4 * d][j] * t.scale, v[4 * d + 1][j] * t.scale, 0, false);
;             r = __builtin_amdgcn_cvt_pk_fp8_f32(v[4 * d + 2][j] * t.scale, v[4 * d + 3][j] * t.scale, r, true); o[d] = (unsigned)r; }
;         *(LAS u32x4*)(tile + (32 * j + i) * 272 + 32 * F.wave + 16 * hi) = o;
;     }
;     __syncthreads();
;     const int c = F.tid & 15;
; #pragma unroll
;     for (int pass = 0; pass < 4; ++pass) { const int n = (F.tid >> 4) + 32 * pass, rho = (n & 3) * 32 + (n >> 2);
;         const u32x4 o = *(const LAS u32x4*)(tile + rho * 272 + 16 * c);
;         *(u32x4*)(t.WT + (size_t)map_row_rt(t.map, t.n0 + n) * D + t.k0 + 16 * c) = o; }
; }
.Lcvw_0:
	v_mul_f32_e32 v132, v10, v1
	v_mov_b32_e32 v130, v199
	v_cvt_pk_fp8_f32 v130, v131, v132
	v_mul_f32_e32 v131, v14, v1
	v_mul_f32_e32 v132, v18, v1
	v_mul_f32_e32 v133, v26, v1
	v_cvt_pk_fp8_f32 v130, v131, v132 op_sel:[0,0,1]
	v_mul_f32_e32 v132, v22, v1
	v_mov_b32_e32 v131, v199
	v_cvt_pk_fp8_f32 v131, v132, v133
	v_mul_f32_e32 v132, v30, v1
	v_mul_f32_e32 v133, v34, v1
	v_mul_f32_e32 v138, v42, v1
	v_cvt_pk_fp8_f32 v131, v132, v133 op_sel:[0,0,1]
	v_mul_f32_e32 v133, v38, v1
	v_mov_b32_e32 v132, v199
	v_cvt_pk_fp8_f32 v132, v133, v138
	v_mul_f32_e32 v133, v46, v1
	v_mul_f32_e32 v138, v50, v1
	v_mul_f32_e32 v139, v58, v1
	v_cvt_pk_fp8_f32 v132, v133, v138 op_sel:[0,0,1]
	v_mul_f32_e32 v138, v54, v1
	v_mov_b32_e32 v133, v199
	v_cvt_pk_fp8_f32 v133, v138, v139
	v_mul_f32_e32 v138, v62, v1
	v_mul_f32_e32 v139, v1, v66
	s_cmp_lt_i32 s8, 1
	v_cvt_pk_fp8_f32 v133, v138, v139 op_sel:[0,0,1]
	v_mul_f32_e32 v138, v43, v1
	v_mul_f32_e32 v139, v59, v1
	ds_write_b128 v144, v[130:133]
	v_mul_f32_e32 v131, v3, v1
	v_mul_f32_e32 v132, v11, v1
	v_mov_b32_e32 v130, v199
	v_cvt_pk_fp8_f32 v130, v131, v132
	v_mul_f32_e32 v131, v15, v1
	v_mul_f32_e32 v132, v19, v1
	v_mul_f32_e32 v133, v27, v1
	v_cvt_pk_fp8_f32 v130, v131, v132 op_sel:[0,0,1]
	v_mul_f32_e32 v132, v23, v1
	v_mov_b32_e32 v131, v199
	v_cvt_pk_fp8_f32 v131, v132, v133
	v_mul_f32_e32 v132, v31, v1
	v_mul_f32_e32 v133, v35, v1
	v_cvt_pk_fp8_f32 v131, v132, v133 op_sel:[0,0,1]
	v_mul_f32_e32 v133, v39, v1
	v_mov_b32_e32 v132, v199
	v_cvt_pk_fp8_f32 v132, v133, v138
	v_mul_f32_e32 v133, v47, v1
	v_mul_f32_e32 v138, v51, v1
	v_cvt_pk_fp8_f32 v132, v133, v138 op_sel:[0,0,1]
	v_mul_f32_e32 v138, v55, v1
	v_mov_b32_e32 v133, v199
	v_cvt_pk_fp8_f32 v133, v138, v139
	v_mul_f32_e32 v138, v63, v1
	v_mul_f32_e32 v139, v1, v67
	v_cvt_pk_fp8_f32 v133, v138, v139 op_sel:[0,0,1]
	v_mul_f32_e32 v138, v44, v1
	v_mul_f32_e32 v139, v60, v1
	ds_write_b128 v144, v[130:133] offset:8704
	v_mul_f32_e32 v131, v4, v1
	v_mul_f32_e32 v132, v12, v1
	v_mov_b32_e32 v130, v199
	v_cvt_pk_fp8_f32 v130, v131, v132
	v_mul_f32_e32 v131, v16, v1
	v_mul_f32_e32 v132, v20, v1
	v_mul_f32_e32 v133, v28, v1
	v_cvt_pk_fp8_f32 v130, v131, v132 op_sel:[0,0,1]
	v_mul_f32_e32 v132, v24, v1
	v_mov_b32_e32 v131, v199
	v_cvt_pk_fp8_f32 v131, v132, v133
	v_mul_f32_e32 v132, v32, v1
	v_mul_f32_e32 v133, v36, v1
	v_cvt_pk_fp8_f32 v131, v132, v133 op_sel:[0,0,1]
	v_mul_f32_e32 v133, v40, v1
	v_mov_b32_e32 v132, v199
	v_cvt_pk_fp8_f32 v132, v133, v138
	v_mul_f32_e32 v133, v48, v1
	v_mul_f32_e32 v138, v52, v1
	v_cvt_pk_fp8_f32 v132, v133, v138 op_sel:[0,0,1]
	v_mul_f32_e32 v138, v56, v1
	v_mov_b32_e32 v133, v199
	v_cvt_pk_fp8_f32 v133, v138, v139
	v_mul_f32_e32 v138, v64, v1
	v_mul_f32_e32 v139, v1, v68
	v_cvt_pk_fp8_f32 v133, v138, v139 op_sel:[0,0,1]
	v_mul_f32_e32 v138, v45, v1
	v_mul_f32_e32 v139, v61, v1
	ds_write_b128 v144, v[130:133] offset:17408
	v_mul_f32_e32 v131, v5, v1
	v_mul_f32_e32 v132, v13, v1
	v_mov_b32_e32 v130, v199
	v_cvt_pk_fp8_f32 v130, v131, v132
	v_mul_f32_e32 v131, v17, v1
	v_mul_f32_e32 v132, v21, v1
	v_mul_f32_e32 v133, v29, v1
	v_cvt_pk_fp8_f32 v130, v131, v132 op_sel:[0,0,1]
	v_mul_f32_e32 v132, v25, v1
	v_mov_b32_e32 v131, v199
	v_cvt_pk_fp8_f32 v131, v132, v133
	v_mul_f32_e32 v132, v33, v1
	v_mul_f32_e32 v133, v37, v1
	v_cvt_pk_fp8_f32 v131, v132, v133 op_sel:[0,0,1]
	v_mul_f32_e32 v133, v41, v1
	v_mov_b32_e32 v132, v199
	v_cvt_pk_fp8_f32 v132, v133, v138
	v_mul_f32_e32 v133, v49, v1
	v_mul_f32_e32 v138, v53, v1
	v_cvt_pk_fp8_f32 v132, v133, v138 op_sel:[0,0,1]
	v_mul_f32_e32 v138, v57, v1
	v_mov_b32_e32 v133, v199
	v_cvt_pk_fp8_f32 v133, v138, v139
	v_mul_f32_e32 v138, v65, v1
	v_mul_f32_e32 v139, v1, v69
	v_cvt_pk_fp8_f32 v133, v138, v139 op_sel:[0,0,1]
	v_add_u32_e32 v139, s28, v137
	ds_write_b128 v144, v[130:133] offset:26112
	s_waitcnt lgkmcnt(0)
	s_barrier
	ds_read_b128 v[130:133], v145
	s_cbranch_scc1 .LBB0_1433
	s_cmp_gt_i32 s8, 2
	s_cbranch_scc0 .LBB0_1434
	s_cmp_eq_u32 s8, 3
	s_mov_b64 s[4:5], -1
	s_cbranch_scc0 .LBB0_1432
	v_lshlrev_b32_e32 v138, 2, v139
	v_lshrrev_b32_e32 v150, 1, v139
	v_and_b32_e32 v138, 16, v138
	v_and_b32_e32 v150, 12, v150
	v_and_b32_e32 v151, 0xffffffe3, v139
	v_or3_b32 v138, v138, v151, v150
	s_mov_b64 s[4:5], 0

; __device__ __forceinline__ float w_qscale(float wmax) { return exp2f(floorf(log2f(128.f / fmaxf(wmax, 1e-30f)))); }
; __device__ __forceinline__ bool witem_decode(const Frame& F, int l, int it, WItem& t) {
;     constexpr int I_GU = 4 * 16, I_DN = 4 * 8, N_GU = NE * I_GU, N_DN = NE * I_DN;
;     const float* wmax = (const float*)((const unsigned*)(F.ws + WS_CTL) + CW_WMAX);
;     int r = it, nblk, item;
;     if (r < N_GU) { const int le = l * NE + r / I_GU; t.W = F.in[16] + (size_t)le * D * 2048; t.WT = (unsigned char*)(F.ws + WS_WGU) + (size_t)le * 2048 * D; t.N = 2048; t.map = 1; nblk = 16; item = r % I_GU; t.scale = w_qscale(wmax[l * 2 + 0]); }
;     else if ((r -= N_GU) < N_DN) { const int le = l * NE + r / I_DN; t.W = F.in[18] + (size_t)le * FF * D; t.WT = (unsigned char*)(F.ws + WS_WDN) + (size_t)le * D * FF; t.N = D; t.map = 3; nblk = 8; item = r % I_DN; t.scale = w_qscale(wmax[l * 2 + 1]); }
;     else return false;
;     t.k0 = 256 * (item / nblk); t.n0 = 128 * (item % nblk); return true;
; }
; __device__ __forceinline__ void witem_load(const WItem& t, int wave, int lane, f32x4 (&v)[16]) {
;     const float* wp = t.W + (size_t)(t.k0 + 32 * wave + 16 * (lane >> 5)) * t.N + t.n0 + 4 * (lane & 31);
; #pragma unroll
;     for (int q = 0; q < 16; ++q) v[q] = __builtin_nontemporal_load((const f32x4*)(wp + (size_t)q * t.N));
; }
; __device__ __forceinline__ void fp8_convert_range(const Frame& F, int l, int start, int stride, int limit) {
;     ...
;     while (ha) {
;         const bool hb = it + stride < limit && witem_decode(F, l, it + stride, tb);
;         if (hb) witem_load(tb, F.wave, F.lane, vb);
;         witem_store(F, ta, va, F.lds);
;         if (!hb) break;
;         it += 2 * stride;
;         ha = it < limit && witem_decode(F, l, it, ta);
;         if (ha) witem_load(ta, F.wave, F.lane, va);
;         witem_store(F, tb, vb, F.lds + 34816);
.LBB0_1496:
	s_load_dword s100, s[4:5], 0x0
	s_mov_b32 s7, 0x43000000
	v_lshlrev_b32_e32 v198, 2, v136
	s_waitcnt lgkmcnt(0)
	v_mov_b32_e32 v1, s100
	v_max_f32_e32 v1, v1, v1
	v_max_f32_e32 v1, 0xda24260, v1
	v_div_scale_f32 v2, s[4:5], v1, v1, s7
	v_rcp_f32_e32 v3, v2
	s_mov_b32 s4, 0x800000
	v_fma_f32 v4, -v2, v3, 1.0
	v_fmac_f32_e32 v3, v4, v3
	v_div_scale_f32 v4, vcc, s7, v1, s7
	v_mul_f32_e32 v5, v4, v3
	v_fma_f32 v10, -v2, v5, v4
	v_fmac_f32_e32 v5, v10, v3
	v_fma_f32 v2, -v2, v5, v4
	v_div_fmas_f32 v2, v2, v3, v5
	v_div_fixup_f32 v1, v2, v1, s7
	v_cmp_gt_f32_e32 vcc, s4, v1
	s_and_b64 s[4:5], vcc, exec
	s_cselect_b32 s4, 32, 0
	v_ldexp_f32 v1, v1, s4
	v_log_f32_e32 v1, v1
	v_cndmask_b32_e32 v2, 0, v232, vcc
	s_mov_b32 s4, 0xc2fc0000
	v_cvt_f32_ubyte0_e32 v3, s6
	v_sub_f32_e32 v1, v1, v2
	v_floor_f32_e32 v1, v1
	v_cmp_gt_f32_e32 vcc, s4, v1
	s_and_b64 s[4:5], vcc, exec
	s_cselect_b32 s4, 0xffffffc0, 0
	v_cndmask_b32_e32 v2, 0, v233, vcc
	v_add_f32_e32 v1, v1, v2
	v_exp_f32_e32 v1, v1
	v_rcp_iflag_f32_e32 v4, v3
	v_ldexp_f32 v1, v1, s4
	s_sext_i32_i8 s4, s3
	v_cvt_f32_i32_e32 v2, s4
	s_ashr_i32 s5, s4, 30
	s_or_b32 s7, s5, 1
	v_mul_f32_e32 v4, v2, v4
	v_trunc_f32_e32 v4, v4
	v_fma_f32 v2, -v4, v3, v2
	v_cvt_i32_f32_e32 v4, v4
	v_cmp_ge_f32_e64 s[4:5], |v2|, v3
	s_and_b64 s[4:5], s[4:5], exec
	s_cselect_b32 s4, s7, 0
	v_readfirstlane_b32 s5, v4
	s_add_i32 s4, s5, s4
	s_sext_i32_i8 s5, s4
	s_mul_i32 s4, s4, s6
	s_lshl_b32 s14, s5, 8
	s_sub_i32 s3, s3, s4
	s_sext_i32_i8 s3, s3
	v_add_u32_e32 v2, s14, v143
	s_lshl_b32 s28, s3, 7
	v_mad_i64_i32 v[2:3], s[4:5], s26, v2, 0
	v_lshl_add_u64 v[2:3], v[2:3], 2, s[50:51]
	s_ashr_i32 s29, s28, 31
	v_lshl_add_u64 v[2:3], s[28:29], 2, v[2:3]
	v_lshl_add_u64 v[10:11], v[2:3], 0, v[198:199]
	s_lshl_b32 s34, s26, 2
	v_lshl_add_u64 v[14:15], v[10:11], 0, s[34:35]
	v_lshl_add_u64 v[18:19], v[14:15], 0, s[34:35]
	v_lshl_add_u64 v[22:23], v[18:19], 0, s[34:35]
	v_lshl_add_u64 v[26:27], v[22:23], 0, s[34:35]
	v_lshl_add_u64 v[30:31], v[26:27], 0, s[34:35]
	v_lshl_add_u64 v[34:35], v[30:31], 0, s[34:35]
	v_lshl_add_u64 v[38:39], v[34:35], 0, s[34:35]
	v_lshl_add_u64 v[42:43], v[38:39], 0, s[34:35]
	v_lshl_add_u64 v[46:47], v[42:43], 0, s[34:35]
	v_lshl_add_u64 v[50:51], v[46:47], 0, s[34:35]
	v_lshl_add_u64 v[54:55], v[50:51], 0, s[34:35]
	v_lshl_add_u64 v[58:59], v[54:55], 0, s[34:35]
	v_lshl_add_u64 v[62:63], v[58:59], 0, s[34:35]
	v_lshl_add_u64 v[66:67], v[62:63], 0, s[34:35]
	global_load_dwordx4 v[2:5], v[10:11], off nt
	s_movk_i32 s29, 0xc00
	global_load_dwordx4 v[10:13], v[14:15], off nt
	s_nop 0
	global_load_dwordx4 v[14:17], v[18:19], off nt
	s_nop 0
	global_load_dwordx4 v[18:21], v[22:23], off nt
	s_nop 0
	global_load_dwordx4 v[22:25], v[26:27], off nt
	s_nop 0
	global_load_dwordx4 v[26:29], v[30:31], off nt
	s_nop 0
	global_load_dwordx4 v[30:33], v[34:35], off nt
	s_nop 0
	global_load_dwordx4 v[34:37], v[38:39], off nt
	s_nop 0
	global_load_dwordx4 v[38:41], v[42:43], off nt
	s_nop 0
	global_load_dwordx4 v[42:45], v[46:47], off nt
	s_nop 0
	global_load_dwordx4 v[46:49], v[50:51], off nt
	s_nop 0
	global_load_dwordx4 v[50:53], v[54:55], off nt
	s_nop 0
	global_load_dwordx4 v[54:57], v[58:59], off nt
	s_nop 0
	global_load_dwordx4 v[58:61], v[62:63], off nt
	s_nop 0
	global_load_dwordx4 v[62:65], v[66:67], off nt
	v_lshl_add_u64 v[66:67], v[66:67], 0, s[34:35]
	global_load_dwordx4 v[66:69], v[66:67], off nt
	s_waitcnt vmcnt(16)
	s_branch .Lcvw_1
.LBB0_1497:
	s_waitcnt vmcnt(0)
; #define LAS __attribute__((address_space(3)))
; __device__ __forceinline__ int map_row_rt(int map, int n) { return map == 0 ? n : (map == 1 ? map_row<1>(n) : (map == 3 ? map_row<3>(n) : map_row<2>(n))); }
; __device__ __forceinline__ void witem_store(const Frame& F, const WItem& t, const f32x4 (&v)[16], LAS unsigned char* tile) {
;     const int i = F.lane & 31, hi = F.lane >> 5;
; #pragma unroll
;     for (int j = 0; j < 4; ++j) {
;         u32x4 o;
; #pragma unroll
;         for (int d = 0; d < 4; ++d) { int r = __builtin_amdgcn_cvt_pk_fp8_f32(v[4 * d][j] * t.scale, v[4 * d + 1][j] * t.scale, 0, false);
;             r = __builtin_amdgcn_cvt_pk_fp8_f32(v[4 * d + 2][j] * t.scale, v[4 * d + 3][j] * t.scale, r, true); o[d] = (unsigned)r; }
;         *(LAS u32x4*)(tile + (32 * j + i) * 272 + 32 * F.wave + 16 * hi) = o;
;     }
;     __syncthreads();
;     const int c = F.tid & 15;
; #pragma unroll
;     for (int pass = 0; pass < 4; ++pass) { const int n = (F.tid >> 4) + 32 * pass, rho = (n & 3) * 32 + (n >> 2);
;         const u32x4 o = *(const LAS u32x4*)(tile + rho * 272 + 16 * c);
;         *(u32x4*)(t.WT + (size_t)map_row_rt(t.map, t.n0 + n) * D + t.k0 + 16 * c) = o; }
; }
.Lcvw_1:
	v_mul_f32_e32 v131, v149, v6
	v_mul_f32_e32 v132, v149, v70
	v_mov_b32_e32 v130, v199
	v_cvt_pk_fp8_f32 v130, v131, v132
	v_mul_f32_e32 v131, v149, v74
	v_mul_f32_e32 v132, v149, v78
	v_mul_f32_e32 v133, v149, v86
	v_cvt_pk_fp8_f32 v130, v131, v132 op_sel:[0,0,1]
	v_mul_f32_e32 v132, v149, v82
	v_mov_b32_e32 v131, v199
	v_cvt_pk_fp8_f32 v131, v132, v133
	v_mul_f32_e32 v132, v149, v90
	v_mul_f32_e32 v133, v149, v94
	v_mul_f32_e32 v138, v149, v102
	v_cvt_pk_fp8_f32 v131, v132, v133 op_sel:[0,0,1]
	v_mul_f32_e32 v133, v149, v98
	v_mov_b32_e32 v132, v199
	v_cvt_pk_fp8_f32 v132, v133, v138
	v_mul_f32_e32 v133, v149, v106
	v_mul_f32_e32 v138, v149, v110
	v_mul_f32_e32 v139, v149, v118
	v_cvt_pk_fp8_f32 v132, v133, v138 op_sel:[0,0,1]
	v_mul_f32_e32 v138, v149, v114
	v_mov_b32_e32 v133, v199
	v_cvt_pk_fp8_f32 v133, v138, v139
	v_mul_f32_e32 v138, v149, v122
	v_mul_f32_e32 v139, v149, v126
	s_cmp_lt_i32 s57, 1
	v_cvt_pk_fp8_f32 v133, v138, v139 op_sel:[0,0,1]
	v_mul_f32_e32 v138, v149, v103
	v_mul_f32_e32 v139, v149, v119
	ds_write_b128 v144, v[130:133] offset:34816
	v_mul_f32_e32 v131, v149, v7
	v_mul_f32_e32 v132, v149, v71
	v_mov_b32_e32 v130, v199
	v_cvt_pk_fp8_f32 v130, v131, v132
	v_mul_f32_e32 v131, v149, v75
	v_mul_f32_e32 v132, v149, v79
	v_mul_f32_e32 v133, v149, v87
	v_cvt_pk_fp8_f32 v130, v131, v132 op_sel:[0,0,1]
	v_mul_f32_e32 v132, v149, v83
	v_mov_b32_e32 v131, v199
	v_cvt_pk_fp8_f32 v131, v132, v133
	v_mul_f32_e32 v132, v149, v91
	v_mul_f32_e32 v133, v149, v95
	v_cvt_pk_fp8_f32 v131, v132, v133 op_sel:[0,0,1]
	v_mul_f32_e32 v133, v149, v99
	v_mov_b32_e32 v132, v199
	v_cvt_pk_fp8_f32 v132, v133, v138
	v_mul_f32_e32 v133, v149, v107
	v_mul_f32_e32 v138, v149, v111
	v_cvt_pk_fp8_f32 v132, v133, v138 op_sel:[0,0,1]
	v_mul_f32_e32 v138, v149, v115
	v_mov_b32_e32 v133, v199
	v_cvt_pk_fp8_f32 v133, v138, v139
	v_mul_f32_e32 v138, v149, v123
	v_mul_f32_e32 v139, v149, v127
	v_cvt_pk_fp8_f32 v133, v138, v139 op_sel:[0,0,1]
	v_mul_f32_e32 v138, v149, v104
	v_mul_f32_e32 v139, v149, v120
	ds_write_b128 v144, v[130:133] offset:43520
	v_mul_f32_e32 v131, v149, v8
	v_mul_f32_e32 v132, v149, v72
	v_mov_b32_e32 v130, v199
	v_cvt_pk_fp8_f32 v130, v131, v132
	v_mul_f32_e32 v131, v149, v76
	v_mul_f32_e32 v132, v149, v80
	v_mul_f32_e32 v133, v149, v88
	v_cvt_pk_fp8_f32 v130, v131, v132 op_sel:[0,0,1]
	v_mul_f32_e32 v132, v149, v84
	v_mov_b32_e32 v131, v199
	v_cvt_pk_fp8_f32 v131, v132, v133
	v_mul_f32_e32 v132, v149, v92
	v_mul_f32_e32 v133, v149, v96
	v_cvt_pk_fp8_f32 v131, v132, v133 op_sel:[0,0,1]
	v_mul_f32_e32 v133, v149, v100
	v_mov_b32_e32 v132, v199
	v_cvt_pk_fp8_f32 v132, v133, v138
	v_mul_f32_e32 v133, v149, v108
	v_mul_f32_e32 v138, v149, v112
	v_cvt_pk_fp8_f32 v132, v133, v138 op_sel:[0,0,1]
	v_mul_f32_e32 v138, v149, v116
	v_mov_b32_e32 v133, v199
	v_cvt_pk_fp8_f32 v133, v138, v139
	v_mul_f32_e32 v138, v149, v124
	v_mul_f32_e32 v139, v149, v128
	v_cvt_pk_fp8_f32 v133, v138, v139 op_sel:[0,0,1]
	v_mul_f32_e32 v138, v149, v105
	v_mul_f32_e32 v139, v149, v121
	ds_write_b128 v144, v[130:133] offset:52224
	v_mul_f32_e32 v131, v149, v9
	v_mul_f32_e32 v132, v149, v73
	v_mov_b32_e32 v130, v199
	v_cvt_pk_fp8_f32 v130, v131, v132
	v_mul_f32_e32 v131, v149, v77
	v_mul_f32_e32 v132, v149, v81
	v_mul_f32_e32 v133, v149, v89
	v_cvt_pk_fp8_f32 v130, v131, v132 op_sel:[0,0,1]
	v_mul_f32_e32 v132, v149, v85
	v_mov_b32_e32 v131, v199
	v_cvt_pk_fp8_f32 v131, v132, v133
	v_mul_f32_e32 v132, v149, v93
	v_mul_f32_e32 v133, v149, v97
	v_cvt_pk_fp8_f32 v131, v132, v133 op_sel:[0,0,1]
	v_mul_f32_e32 v133, v149, v101
	v_mov_b32_e32 v132, v199
	v_cvt_pk_fp8_f32 v132, v133, v138
	v_mul_f32_e32 v133, v149, v109
	v_mul_f32_e32 v138, v149, v113
	v_cvt_pk_fp8_f32 v132, v133, v138 op_sel:[0,0,1]
	v_mul_f32_e32 v138, v149, v117
	v_mov_b32_e32 v133, v199
	v_cvt_pk_fp8_f32 v133, v138, v139
	v_mul_f32_e32 v138, v149, v125
	v_mul_f32_e32 v139, v149, v129
	v_cvt_pk_fp8_f32 v133, v138, v139 op_sel:[0,0,1]
	v_add_u32_e32 v139, s46, v137
	ds_write_b128 v144, v[130:133] offset:60928
	s_waitcnt lgkmcnt(0)
	s_barrier
	ds_read_b128 v[130:133], v145 offset:34816
	s_cbranch_scc1 .LBB0_1502
	s_cmp_gt_i32 s57, 2
	s_cbranch_scc0 .LBB0_1503
	s_cmp_eq_u32 s57, 3
	s_mov_b64 s[4:5], -1
	s_cbranch_scc0 .LBB0_1501
	v_lshlrev_b32_e32 v138, 2, v139
	v_lshrrev_b32_e32 v150, 1, v139
	v_and_b32_e32 v138, 16, v138
	v_and_b32_e32 v150, 12, v150
	v_and_b32_e32 v151, 0xffffffe3, v139
	v_or3_b32 v138, v138, v151, v150
	s_mov_b64 s[4:5], 0

; __device__ __forceinline__ float w_qscale(float wmax) { return exp2f(floorf(log2f(128.f / fmaxf(wmax, 1e-30f)))); }
; __device__ __forceinline__ bool witem_decode(const Frame& F, int l, int it, WItem& t) {
;     constexpr int I_GU = 4 * 16, I_DN = 4 * 8, N_GU = NE * I_GU, N_DN = NE * I_DN;
;     const float* wmax = (const float*)((const unsigned*)(F.ws + WS_CTL) + CW_WMAX);
;     int r = it, nblk, item;
;     if (r < N_GU) { const int le = l * NE + r / I_GU; t.W = F.in[16] + (size_t)le * D * 2048; t.WT = (unsigned char*)(F.ws + WS_WGU) + (size_t)le * 2048 * D; t.N = 2048; t.map = 1; nblk = 16; item = r % I_GU; t.scale = w_qscale(wmax[l * 2 + 0]); }
;     else if ((r -= N_GU) < N_DN) { const int le = l * NE + r / I_DN; t.W = F.in[18] + (size_t)le * FF * D; t.WT = (unsigned char*)(F.ws + WS_WDN) + (size_t)le * D * FF; t.N = D; t.map = 3; nblk = 8; item = r % I_DN; t.scale = w_qscale(wmax[l * 2 + 1]); }
;     else return false;
;     t.k0 = 256 * (item / nblk); t.n0 = 128 * (item % nblk); return true;
; }
; __device__ __forceinline__ void witem_load(const WItem& t, int wave, int lane, f32x4 (&v)[16]) {
;     const float* wp = t.W + (size_t)(t.k0 + 32 * wave + 16 * (lane >> 5)) * t.N + t.n0 + 4 * (lane & 31);
; #pragma unroll
;     for (int q = 0; q < 16; ++q) v[q] = __builtin_nontemporal_load((const f32x4*)(wp + (size_t)q * t.N));
; }
; __device__ __forceinline__ void fp8_convert_range(const Frame& F, int l, int start, int stride, int limit) {
;     ...
;     WItem ta, tb; f32x4 va[16], vb[16];
;     int it = start;
;     bool ha = it < limit && witem_decode(F, l, it, ta);
;     if (ha) witem_load(ta, F.wave, F.lane, va);
;     while (ha) {
;         const bool hb = it + stride < limit && witem_decode(F, l, it + stride, tb);
;         if (hb) witem_load(tb, F.wave, F.lane, vb);
.LBB0_1613:
	s_load_dword s100, s[4:5], 0x0
	s_mov_b32 s7, 0x43000000
	v_lshlrev_b32_e32 v198, 2, v136
	s_waitcnt lgkmcnt(0)
	v_mov_b32_e32 v6, s100
	v_max_f32_e32 v6, v6, v6
	v_max_f32_e32 v6, 0xda24260, v6
	v_div_scale_f32 v7, s[4:5], v6, v6, s7
	v_rcp_f32_e32 v8, v7
	s_mov_b32 s4, 0x800000
	v_fma_f32 v9, -v7, v8, 1.0
	v_fmac_f32_e32 v8, v9, v8
	v_div_scale_f32 v9, vcc, s7, v6, s7
	v_mul_f32_e32 v70, v9, v8
	v_fma_f32 v71, -v7, v70, v9
	v_fmac_f32_e32 v70, v71, v8
	v_fma_f32 v7, -v7, v70, v9
	v_div_fmas_f32 v7, v7, v8, v70
	v_div_fixup_f32 v6, v7, v6, s7
	v_cmp_gt_f32_e32 vcc, s4, v6
	s_and_b64 s[4:5], vcc, exec
	s_cselect_b32 s4, 32, 0
	v_ldexp_f32 v6, v6, s4
	v_log_f32_e32 v6, v6
	v_cndmask_b32_e32 v7, 0, v232, vcc
	s_mov_b32 s4, 0xc2fc0000
	v_sub_f32_e32 v6, v6, v7
	v_floor_f32_e32 v6, v6
	v_cmp_gt_f32_e32 vcc, s4, v6
	s_and_b64 s[4:5], vcc, exec
	s_cselect_b32 s4, 0xffffffc0, 0
	v_cndmask_b32_e32 v7, 0, v233, vcc
	v_add_f32_e32 v6, v6, v7
	v_exp_f32_e32 v6, v6
	v_cvt_f32_ubyte0_e32 v7, s6
	v_rcp_iflag_f32_e32 v8, v7
	v_ldexp_f32 v149, v6, s4
	s_sext_i32_i8 s4, s3
	v_cvt_f32_i32_e32 v6, s4
	s_ashr_i32 s5, s4, 30
	s_or_b32 s7, s5, 1
	v_mul_f32_e32 v8, v6, v8
	v_trunc_f32_e32 v8, v8
	v_fma_f32 v6, -v8, v7, v6
	v_cvt_i32_f32_e32 v8, v8
	v_cmp_ge_f32_e64 s[4:5], |v6|, v7
	s_and_b64 s[4:5], s[4:5], exec
	s_cselect_b32 s4, s7, 0
	v_readfirstlane_b32 s5, v8
	s_add_i32 s4, s5, s4
	s_sext_i32_i8 s5, s4
	s_mul_i32 s4, s4, s6
	s_lshl_b32 s46, s5, 8
	s_sub_i32 s3, s3, s4
	s_sext_i32_i8 s3, s3
	v_add_u32_e32 v6, s46, v143
	s_lshl_b32 s48, s3, 7
	v_mad_i64_i32 v[6:7], s[4:5], s26, v6, 0
	v_lshl_add_u64 v[6:7], v[6:7], 2, s[52:53]
	s_ashr_i32 s49, s48, 31
	v_lshl_add_u64 v[6:7], s[48:49], 2, v[6:7]
	v_lshl_add_u64 v[70:71], v[6:7], 0, v[198:199]
	s_lshl_b32 s34, s26, 2
	v_lshl_add_u64 v[74:75], v[70:71], 0, s[34:35]
	v_lshl_add_u64 v[78:79], v[74:75], 0, s[34:35]
	v_lshl_add_u64 v[82:83], v[78:79], 0, s[34:35]
	v_lshl_add_u64 v[86:87], v[82:83], 0, s[34:35]
	v_lshl_add_u64 v[90:91], v[86:87], 0, s[34:35]
	v_lshl_add_u64 v[94:95], v[90:91], 0, s[34:35]
	v_lshl_add_u64 v[98:99], v[94:95], 0, s[34:35]
	v_lshl_add_u64 v[102:103], v[98:99], 0, s[34:35]
	v_lshl_add_u64 v[106:107], v[102:103], 0, s[34:35]
	v_lshl_add_u64 v[110:111], v[106:107], 0, s[34:35]
	v_lshl_add_u64 v[114:115], v[110:111], 0, s[34:35]
	v_lshl_add_u64 v[118:119], v[114:115], 0, s[34:35]
	v_lshl_add_u64 v[122:123], v[118:119], 0, s[34:35]
	v_lshl_add_u64 v[126:127], v[122:123], 0, s[34:35]
	global_load_dwordx4 v[6:9], v[70:71], off nt
	s_nop 0
	global_load_dwordx4 v[70:73], v[74:75], off nt
	s_nop 0
	global_load_dwordx4 v[74:77], v[78:79], off nt
	s_nop 0
	global_load_dwordx4 v[78:81], v[82:83], off nt
	s_nop 0
	global_load_dwordx4 v[82:85], v[86:87], off nt
	s_nop 0
	global_load_dwordx4 v[86:89], v[90:91], off nt
	s_nop 0
	global_load_dwordx4 v[90:93], v[94:95], off nt
	s_nop 0
	global_load_dwordx4 v[94:97], v[98:99], off nt
	s_nop 0
	global_load_dwordx4 v[98:101], v[102:103], off nt
	s_nop 0
	global_load_dwordx4 v[102:105], v[106:107], off nt
	s_nop 0
	global_load_dwordx4 v[106:109], v[110:111], off nt
	s_nop 0
	global_load_dwordx4 v[110:113], v[114:115], off nt
	s_nop 0
	global_load_dwordx4 v[114:117], v[118:119], off nt
	s_nop 0
	global_load_dwordx4 v[118:121], v[122:123], off nt
	s_nop 0
	global_load_dwordx4 v[122:125], v[126:127], off nt
	v_lshl_add_u64 v[126:127], v[126:127], 0, s[34:35]
	global_load_dwordx4 v[126:129], v[126:127], off nt
	s_waitcnt vmcnt(16)
	v_mul_f32_e32 v131, v2, v1
	s_branch .Lcvw_2

; #define LAS __attribute__((address_space(3)))
; __device__ __forceinline__ int map_row_rt(int map, int n) { return map == 0 ? n : (map == 1 ? map_row<1>(n) : (map == 3 ? map_row<3>(n) : map_row<2>(n))); }
; __device__ __forceinline__ void witem_store(const Frame& F, const WItem& t, const f32x4 (&v)[16], LAS unsigned char* tile) {
;     const int i = F.lane & 31, hi = F.lane >> 5;
; #pragma unroll
;     for (int j = 0; j < 4; ++j) {
;         u32x4 o;
; #pragma unroll
;         for (int d = 0; d < 4; ++d) { int r = __builtin_amdgcn_cvt_pk_fp8_f32(v[4 * d][j] * t.scale, v[4 * d + 1][j] * t.scale, 0, false);
;             r = __builtin_amdgcn_cvt_pk_fp8_f32(v[4 * d + 2][j] * t.scale, v[4 * d + 3][j] * t.scale, r, true); o[d] = (unsigned)r; }
;         *(LAS u32x4*)(tile + (32 * j + i) * 272 + 32 * F.wave + 16 * hi) = o;
;     }
;     __syncthreads();
;     const int c = F.tid & 15;
; #pragma unroll
;     for (int pass = 0; pass < 4; ++pass) { const int n = (F.tid >> 4) + 32 * pass, rho = (n & 3) * 32 + (n >> 2);
;         const u32x4 o = *(const LAS u32x4*)(tile + rho * 272 + 16 * c);
;         *(u32x4*)(t.WT + (size_t)map_row_rt(t.map, t.n0 + n) * D + t.k0 + 16 * c) = o; }
; }
.Lcvw_2:
	v_mul_f32_e32 v132, v10, v1
	v_mov_b32_e32 v130, v199
	v_cvt_pk_fp8_f32 v130, v131, v132
	v_mul_f32_e32 v131, v14, v1
	v_mul_f32_e32 v132, v18, v1
	v_mul_f32_e32 v133, v26, v1
	v_cvt_pk_fp8_f32 v130, v131, v132 op_sel:[0,0,1]
	v_mul_f32_e32 v132, v22, v1
	v_mov_b32_e32 v131, v199
	v_cvt_pk_fp8_f32 v131, v132, v133
	v_mul_f32_e32 v132, v30, v1
	v_mul_f32_e32 v133, v34, v1
	v_mul_f32_e32 v138, v42, v1
	v_cvt_pk_fp8_f32 v131, v132, v133 op_sel:[0,0,1]
	v_mul_f32_e32 v133, v38, v1
	v_mov_b32_e32 v132, v199
	v_cvt_pk_fp8_f32 v132, v133, v138
	v_mul_f32_e32 v133, v46, v1
	v_mul_f32_e32 v138, v50, v1
	v_mul_f32_e32 v139, v58, v1
	v_cvt_pk_fp8_f32 v132, v133, v138 op_sel:[0,0,1]
	v_mul_f32_e32 v138, v54, v1
	v_mov_b32_e32 v133, v199
	v_cvt_pk_fp8_f32 v133, v138, v139
	v_mul_f32_e32 v138, v62, v1
	v_mul_f32_e32 v139, v1, v66
	s_cmp_lt_i32 s8, 1
	v_cvt_pk_fp8_f32 v133, v138, v139 op_sel:[0,0,1]
	v_mul_f32_e32 v138, v43, v1
	v_mul_f32_e32 v139, v59, v1
	ds_write_b128 v144, v[130:133]
	v_mul_f32_e32 v131, v3, v1
	v_mul_f32_e32 v132, v11, v1
	v_mov_b32_e32 v130, v199
	v_cvt_pk_fp8_f32 v130, v131, v132
	v_mul_f32_e32 v131, v15, v1
	v_mul_f32_e32 v132, v19, v1
	v_mul_f32_e32 v133, v27, v1
	v_cvt_pk_fp8_f32 v130, v131, v132 op_sel:[0,0,1]
	v_mul_f32_e32 v132, v23, v1
	v_mov_b32_e32 v131, v199
	v_cvt_pk_fp8_f32 v131, v132, v133
	v_mul_f32_e32 v132, v31, v1
	v_mul_f32_e32 v133, v35, v1
	v_cvt_pk_fp8_f32 v131, v132, v133 op_sel:[0,0,1]
	v_mul_f32_e32 v133, v39, v1
	v_mov_b32_e32 v132, v199
	v_cvt_pk_fp8_f32 v132, v133, v138
	v_mul_f32_e32 v133, v47, v1
	v_mul_f32_e32 v138, v51, v1
	v_cvt_pk_fp8_f32 v132, v133, v138 op_sel:[0,0,1]
	v_mul_f32_e32 v138, v55, v1
	v_mov_b32_e32 v133, v199
	v_cvt_pk_fp8_f32 v133, v138, v139
	v_mul_f32_e32 v138, v63, v1
	v_mul_f32_e32 v139, v1, v67
	v_cvt_pk_fp8_f32 v133, v138, v139 op_sel:[0,0,1]
	v_mul_f32_e32 v138, v44, v1
	v_mul_f32_e32 v139, v60, v1
	ds_write_b128 v144, v[130:133] offset:8704
	v_mul_f32_e32 v131, v4, v1
	v_mul_f32_e32 v132, v12, v1
	v_mov_b32_e32 v130, v199
	v_cvt_pk_fp8_f32 v130, v131, v132
	v_mul_f32_e32 v131, v16, v1
	v_mul_f32_e32 v132, v20, v1
	v_mul_f32_e32 v133, v28, v1
	v_cvt_pk_fp8_f32 v130, v131, v132 op_sel:[0,0,1]
	v_mul_f32_e32 v132, v24, v1
	v_mov_b32_e32 v131, v199
	v_cvt_pk_fp8_f32 v131, v132, v133
	v_mul_f32_e32 v132, v32, v1
	v_mul_f32_e32 v133, v36, v1
	v_cvt_pk_fp8_f32 v131, v132, v133 op_sel:[0,0,1]
	v_mul_f32_e32 v133, v40, v1
	v_mov_b32_e32 v132, v199
	v_cvt_pk_fp8_f32 v132, v133, v138
	v_mul_f32_e32 v133, v48, v1
	v_mul_f32_e32 v138, v52, v1
	v_cvt_pk_fp8_f32 v132, v133, v138 op_sel:[0,0,1]
	v_mul_f32_e32 v138, v56, v1
	v_mov_b32_e32 v133, v199
	v_cvt_pk_fp8_f32 v133, v138, v139
	v_mul_f32_e32 v138, v64, v1
	v_mul_f32_e32 v139, v1, v68
	v_cvt_pk_fp8_f32 v133, v138, v139 op_sel:[0,0,1]
	v_mul_f32_e32 v138, v45, v1
	v_mul_f32_e32 v139, v61, v1
	ds_write_b128 v144, v[130:133] offset:17408
	v_mul_f32_e32 v131, v5, v1
	v_mul_f32_e32 v132, v13, v1
	v_mov_b32_e32 v130, v199
	v_cvt_pk_fp8_f32 v130, v131, v132
	v_mul_f32_e32 v131, v17, v1
	v_mul_f32_e32 v132, v21, v1
	v_mul_f32_e32 v133, v29, v1
	v_cvt_pk_fp8_f32 v130, v131, v132 op_sel:[0,0,1]
	v_mul_f32_e32 v132, v25, v1
	v_mov_b32_e32 v131, v199
	v_cvt_pk_fp8_f32 v131, v132, v133
	v_mul_f32_e32 v132, v33, v1
	v_mul_f32_e32 v133, v37, v1
	v_cvt_pk_fp8_f32 v131, v132, v133 op_sel:[0,0,1]
	v_mul_f32_e32 v133, v41, v1
	v_mov_b32_e32 v132, v199
	v_cvt_pk_fp8_f32 v132, v133, v138
	v_mul_f32_e32 v133, v49, v1
	v_mul_f32_e32 v138, v53, v1
	v_cvt_pk_fp8_f32 v132, v133, v138 op_sel:[0,0,1]
	v_mul_f32_e32 v138, v57, v1
	v_mov_b32_e32 v133, v199
	v_cvt_pk_fp8_f32 v133, v138, v139
	v_mul_f32_e32 v138, v65, v1
	v_mul_f32_e32 v139, v1, v69
	v_cvt_pk_fp8_f32 v133, v138, v139 op_sel:[0,0,1]
	v_add_u32_e32 v139, s36, v137
	ds_write_b128 v144, v[130:133] offset:26112
	s_waitcnt lgkmcnt(0)
	s_barrier
	ds_read_b128 v[130:133], v145
	s_cbranch_scc1 .LBB0_1619
	s_cmp_gt_i32 s8, 2
	s_cbranch_scc0 .LBB0_1620
	s_cmp_eq_u32 s8, 3
	s_mov_b64 s[4:5], -1
	s_cbranch_scc0 .LBB0_1618
	v_lshlrev_b32_e32 v138, 2, v139
	v_lshrrev_b32_e32 v150, 1, v139
	v_and_b32_e32 v138, 16, v138
	v_and_b32_e32 v150, 12, v150
	v_and_b32_e32 v151, 0xffffffe3, v139
	v_or3_b32 v138, v138, v151, v150
	s_mov_b64 s[4:5], 0

; __device__ __forceinline__ float w_qscale(float wmax) { return exp2f(floorf(log2f(128.f / fmaxf(wmax, 1e-30f)))); }
; __device__ __forceinline__ bool witem_decode(const Frame& F, int l, int it, WItem& t) {
;     constexpr int I_GU = 4 * 16, I_DN = 4 * 8, N_GU = NE * I_GU, N_DN = NE * I_DN;
;     const float* wmax = (const float*)((const unsigned*)(F.ws + WS_CTL) + CW_WMAX);
;     int r = it, nblk, item;
;     if (r < N_GU) { const int le = l * NE + r / I_GU; t.W = F.in[16] + (size_t)le * D * 2048; t.WT = (unsigned char*)(F.ws + WS_WGU) + (size_t)le * 2048 * D; t.N = 2048; t.map = 1; nblk = 16; item = r % I_GU; t.scale = w_qscale(wmax[l * 2 + 0]); }
;     else if ((r -= N_GU) < N_DN) { const int le = l * NE + r / I_DN; t.W = F.in[18] + (size_t)le * FF * D; t.WT = (unsigned char*)(F.ws + WS_WDN) + (size_t)le * D * FF; t.N = D; t.map = 3; nblk = 8; item = r % I_DN; t.scale = w_qscale(wmax[l * 2 + 1]); }
;     else return false;
;     t.k0 = 256 * (item / nblk); t.n0 = 128 * (item % nblk); return true;
; }
; __device__ __forceinline__ void witem_load(const WItem& t, int wave, int lane, f32x4 (&v)[16]) {
;     const float* wp = t.W + (size_t)(t.k0 + 32 * wave + 16 * (lane >> 5)) * t.N + t.n0 + 4 * (lane & 31);
; #pragma unroll
;     for (int q = 0; q < 16; ++q) v[q] = __builtin_nontemporal_load((const f32x4*)(wp + (size_t)q * t.N));
; }
; __device__ __forceinline__ void fp8_convert_range(const Frame& F, int l, int start, int stride, int limit) {
;     ...
;     while (ha) {
;         const bool hb = it + stride < limit && witem_decode(F, l, it + stride, tb);
;         if (hb) witem_load(tb, F.wave, F.lane, vb);
;         witem_store(F, ta, va, F.lds);
;         if (!hb) break;
;         it += 2 * stride;
;         ha = it < limit && witem_decode(F, l, it, ta);
;         if (ha) witem_load(ta, F.wave, F.lane, va);
;         witem_store(F, tb, vb, F.lds + 34816);
.LBB0_1682:
	s_load_dword s100, s[4:5], 0x0
	s_mov_b32 s7, 0x43000000
	v_lshlrev_b32_e32 v198, 2, v136
	s_waitcnt lgkmcnt(0)
	v_mov_b32_e32 v1, s100
	v_max_f32_e32 v1, v1, v1
	v_max_f32_e32 v1, 0xda24260, v1
	v_div_scale_f32 v2, s[4:5], v1, v1, s7
	v_rcp_f32_e32 v3, v2
	s_mov_b32 s4, 0x800000
	v_fma_f32 v4, -v2, v3, 1.0
	v_fmac_f32_e32 v3, v4, v3
	v_div_scale_f32 v4, vcc, s7, v1, s7
	v_mul_f32_e32 v5, v4, v3
	v_fma_f32 v10, -v2, v5, v4
	v_fmac_f32_e32 v5, v10, v3
	v_fma_f32 v2, -v2, v5, v4
	v_div_fmas_f32 v2, v2, v3, v5
	v_div_fixup_f32 v1, v2, v1, s7
	v_cmp_gt_f32_e32 vcc, s4, v1
	s_and_b64 s[4:5], vcc, exec
	s_cselect_b32 s4, 32, 0
	v_ldexp_f32 v1, v1, s4
	v_log_f32_e32 v1, v1
	v_cndmask_b32_e32 v2, 0, v232, vcc
	s_mov_b32 s4, 0xc2fc0000
	v_cvt_f32_ubyte0_e32 v3, s6
	v_sub_f32_e32 v1, v1, v2
	v_floor_f32_e32 v1, v1
	v_cmp_gt_f32_e32 vcc, s4, v1
	s_and_b64 s[4:5], vcc, exec
	s_cselect_b32 s4, 0xffffffc0, 0
	v_cndmask_b32_e32 v2, 0, v233, vcc
	v_add_f32_e32 v1, v1, v2
	v_exp_f32_e32 v1, v1
	v_rcp_iflag_f32_e32 v4, v3
	v_ldexp_f32 v1, v1, s4
	s_sext_i32_i8 s4, s3
	v_cvt_f32_i32_e32 v2, s4
	s_ashr_i32 s5, s4, 30
	s_or_b32 s7, s5, 1
	v_mul_f32_e32 v4, v2, v4
	v_trunc_f32_e32 v4, v4
	v_fma_f32 v2, -v4, v3, v2
	v_cvt_i32_f32_e32 v4, v4
	v_cmp_ge_f32_e64 s[4:5], |v2|, v3
	s_and_b64 s[4:5], s[4:5], exec
	s_cselect_b32 s4, s7, 0
	v_readfirstlane_b32 s5, v4
	s_add_i32 s4, s5, s4
	s_sext_i32_i8 s5, s4
	s_mul_i32 s4, s4, s6
	s_lshl_b32 s28, s5, 8
	s_sub_i32 s3, s3, s4
	s_sext_i32_i8 s3, s3
	v_add_u32_e32 v2, s28, v143
	s_lshl_b32 s36, s3, 7
	v_mad_i64_i32 v[2:3], s[4:5], s26, v2, 0
	v_lshl_add_u64 v[2:3], v[2:3], 2, s[52:53]
	s_ashr_i32 s37, s36, 31
	v_lshl_add_u64 v[2:3], s[36:37], 2, v[2:3]
	v_lshl_add_u64 v[10:11], v[2:3], 0, v[198:199]
	s_lshl_b32 s34, s26, 2
	v_lshl_add_u64 v[14:15], v[10:11], 0, s[34:35]
	v_lshl_add_u64 v[18:19], v[14:15], 0, s[34:35]
	v_lshl_add_u64 v[22:23], v[18:19], 0, s[34:35]
	v_lshl_add_u64 v[26:27], v[22:23], 0, s[34:35]
	v_lshl_add_u64 v[30:31], v[26:27], 0, s[34:35]
	v_lshl_add_u64 v[34:35], v[30:31], 0, s[34:35]
	v_lshl_add_u64 v[38:39], v[34:35], 0, s[34:35]
	v_lshl_add_u64 v[42:43], v[38:39], 0, s[34:35]
	v_lshl_add_u64 v[46:47], v[42:43], 0, s[34:35]
	v_lshl_add_u64 v[50:51], v[46:47], 0, s[34:35]
	v_lshl_add_u64 v[54:55], v[50:51], 0, s[34:35]
	v_lshl_add_u64 v[58:59], v[54:55], 0, s[34:35]
	v_lshl_add_u64 v[62:63], v[58:59], 0, s[34:35]
	v_lshl_add_u64 v[66:67], v[62:63], 0, s[34:35]
	global_load_dwordx4 v[2:5], v[10:11], off nt
	s_nop 0
	global_load_dwordx4 v[10:13], v[14:15], off nt
	s_nop 0
	global_load_dwordx4 v[14:17], v[18:19], off nt
	s_nop 0
	global_load_dwordx4 v[18:21], v[22:23], off nt
	s_nop 0
	global_load_dwordx4 v[22:25], v[26:27], off nt
	s_nop 0
	global_load_dwordx4 v[26:29], v[30:31], off nt
	s_nop 0
	global_load_dwordx4 v[30:33], v[34:35], off nt
	s_nop 0
	global_load_dwordx4 v[34:37], v[38:39], off nt
	s_nop 0
	global_load_dwordx4 v[38:41], v[42:43], off nt
	s_nop 0
	global_load_dwordx4 v[42:45], v[46:47], off nt
	s_nop 0
	global_load_dwordx4 v[46:49], v[50:51], off nt
	s_nop 0
	global_load_dwordx4 v[50:53], v[54:55], off nt
	s_nop 0
	global_load_dwordx4 v[54:57], v[58:59], off nt
	s_nop 0
	global_load_dwordx4 v[58:61], v[62:63], off nt
	s_nop 0
	global_load_dwordx4 v[62:65], v[66:67], off nt
	v_lshl_add_u64 v[66:67], v[66:67], 0, s[34:35]
	global_load_dwordx4 v[66:69], v[66:67], off nt
	s_waitcnt vmcnt(16)
	s_branch .Lcvw_3
.LBB0_1683:
	s_waitcnt vmcnt(0)
; #define LAS __attribute__((address_space(3)))
; __device__ __forceinline__ int map_row_rt(int map, int n) { return map == 0 ? n : (map == 1 ? map_row<1>(n) : (map == 3 ? map_row<3>(n) : map_row<2>(n))); }
; __device__ __forceinline__ void witem_store(const Frame& F, const WItem& t, const f32x4 (&v)[16], LAS unsigned char* tile) {
;     const int i = F.lane & 31, hi = F.lane >> 5;
; #pragma unroll
;     for (int j = 0; j < 4; ++j) {
;         u32x4 o;
; #pragma unroll
;         for (int d = 0; d < 4; ++d) { int r = __builtin_amdgcn_cvt_pk_fp8_f32(v[4 * d][j] * t.scale, v[4 * d + 1][j] * t.scale, 0, false);
;             r = __builtin_amdgcn_cvt_pk_fp8_f32(v[4 * d + 2][j] * t.scale, v[4 * d + 3][j] * t.scale, r, true); o[d] = (unsigned)r; }
;         *(LAS u32x4*)(tile + (32 * j + i) * 272 + 32 * F.wave + 16 * hi) = o;
;     }
;     __syncthreads();
;     const int c = F.tid & 15;
; #pragma unroll
;     for (int pass = 0; pass < 4; ++pass) { const int n = (F.tid >> 4) + 32 * pass, rho = (n & 3) * 32 + (n >> 2);
;         const u32x4 o = *(const LAS u32x4*)(tile + rho * 272 + 16 * c);
;         *(u32x4*)(t.WT + (size_t)map_row_rt(t.map, t.n0 + n) * D + t.k0 + 16 * c) = o; }
; }
.Lcvw_3:
	v_mul_f32_e32 v131, v149, v6
	v_mul_f32_e32 v132, v149, v70
	v_mov_b32_e32 v130, v199
	v_cvt_pk_fp8_f32 v130, v131, v132
	v_mul_f32_e32 v131, v149, v74
	v_mul_f32_e32 v132, v149, v78
	v_mul_f32_e32 v133, v149, v86
	v_cvt_pk_fp8_f32 v130, v131, v132 op_sel:[0,0,1]
	v_mul_f32_e32 v132, v149, v82
	v_mov_b32_e32 v131, v199
	v_cvt_pk_fp8_f32 v131, v132, v133
	v_mul_f32_e32 v132, v149, v90
	v_mul_f32_e32 v133, v149, v94
	v_mul_f32_e32 v138, v149, v102
	v_cvt_pk_fp8_f32 v131, v132, v133 op_sel:[0,0,1]
	v_mul_f32_e32 v133, v149, v98
	v_mov_b32_e32 v132, v199
	v_cvt_pk_fp8_f32 v132, v133, v138
	v_mul_f32_e32 v133, v149, v106
	v_mul_f32_e32 v138, v149, v110
	v_mul_f32_e32 v139, v149, v118
	v_cvt_pk_fp8_f32 v132, v133, v138 op_sel:[0,0,1]
	v_mul_f32_e32 v138, v149, v114
	v_mov_b32_e32 v133, v199
	v_cvt_pk_fp8_f32 v133, v138, v139
	v_mul_f32_e32 v138, v149, v122
	v_mul_f32_e32 v139, v149, v126
	s_cmp_lt_i32 s58, 1
	v_cvt_pk_fp8_f32 v133, v138, v139 op_sel:[0,0,1]
	v_mul_f32_e32 v138, v149, v103
	v_mul_f32_e32 v139, v149, v119
	ds_write_b128 v144, v[130:133] offset:34816
	v_mul_f32_e32 v131, v149, v7
	v_mul_f32_e32 v132, v149, v71
	v_mov_b32_e32 v130, v199
	v_cvt_pk_fp8_f32 v130, v131, v132
	v_mul_f32_e32 v131, v149, v75
	v_mul_f32_e32 v132, v149, v79
	v_mul_f32_e32 v133, v149, v87
	v_cvt_pk_fp8_f32 v130, v131, v132 op_sel:[0,0,1]
	v_mul_f32_e32 v132, v149, v83
	v_mov_b32_e32 v131, v199
	v_cvt_pk_fp8_f32 v131, v132, v133
	v_mul_f32_e32 v132, v149, v91
	v_mul_f32_e32 v133, v149, v95
	v_cvt_pk_fp8_f32 v131, v132, v133 op_sel:[0,0,1]
	v_mul_f32_e32 v133, v149, v99
	v_mov_b32_e32 v132, v199
	v_cvt_pk_fp8_f32 v132, v133, v138
	v_mul_f32_e32 v133, v149, v107
	v_mul_f32_e32 v138, v149, v111
	v_cvt_pk_fp8_f32 v132, v133, v138 op_sel:[0,0,1]
	v_mul_f32_e32 v138, v149, v115
	v_mov_b32_e32 v133, v199
	v_cvt_pk_fp8_f32 v133, v138, v139
	v_mul_f32_e32 v138, v149, v123
	v_mul_f32_e32 v139, v149, v127
	v_cvt_pk_fp8_f32 v133, v138, v139 op_sel:[0,0,1]
	v_mul_f32_e32 v138, v149, v104
	v_mul_f32_e32 v139, v149, v120
	ds_write_b128 v144, v[130:133] offset:43520
	v_mul_f32_e32 v131, v149, v8
	v_mul_f32_e32 v132, v149, v72
	v_mov_b32_e32 v130, v199
	v_cvt_pk_fp8_f32 v130, v131, v132
	v_mul_f32_e32 v131, v149, v76
	v_mul_f32_e32 v132, v149, v80
	v_mul_f32_e32 v133, v149, v88
	v_cvt_pk_fp8_f32 v130, v131, v132 op_sel:[0,0,1]
	v_mul_f32_e32 v132, v149, v84
	v_mov_b32_e32 v131, v199
	v_cvt_pk_fp8_f32 v131, v132, v133
	v_mul_f32_e32 v132, v149, v92
	v_mul_f32_e32 v133, v149, v96
	v_cvt_pk_fp8_f32 v131, v132, v133 op_sel:[0,0,1]
	v_mul_f32_e32 v133, v149, v100
	v_mov_b32_e32 v132, v199
	v_cvt_pk_fp8_f32 v132, v133, v138
	v_mul_f32_e32 v133, v149, v108
	v_mul_f32_e32 v138, v149, v112
	v_cvt_pk_fp8_f32 v132, v133, v138 op_sel:[0,0,1]
	v_mul_f32_e32 v138, v149, v116
	v_mov_b32_e32 v133, v199
	v_cvt_pk_fp8_f32 v133, v138, v139
	v_mul_f32_e32 v138, v149, v124
	v_mul_f32_e32 v139, v149, v128
	v_cvt_pk_fp8_f32 v133, v138, v139 op_sel:[0,0,1]
	v_mul_f32_e32 v138, v149, v105
	v_mul_f32_e32 v139, v149, v121
	ds_write_b128 v144, v[130:133] offset:52224
	v_mul_f32_e32 v131, v149, v9
	v_mul_f32_e32 v132, v149, v73
	v_mov_b32_e32 v130, v199
	v_cvt_pk_fp8_f32 v130, v131, v132
	v_mul_f32_e32 v131, v149, v77
	v_mul_f32_e32 v132, v149, v81
	v_mul_f32_e32 v133, v149, v89
	v_cvt_pk_fp8_f32 v130, v131, v132 op_sel:[0,0,1]
	v_mul_f32_e32 v132, v149, v85
	v_mov_b32_e32 v131, v199
	v_cvt_pk_fp8_f32 v131, v132, v133
	v_mul_f32_e32 v132, v149, v93
	v_mul_f32_e32 v133, v149, v97
	v_cvt_pk_fp8_f32 v131, v132, v133 op_sel:[0,0,1]
	v_mul_f32_e32 v133, v149, v101
	v_mov_b32_e32 v132, v199
	v_cvt_pk_fp8_f32 v132, v133, v138
	v_mul_f32_e32 v133, v149, v109
	v_mul_f32_e32 v138, v149, v113
	v_cvt_pk_fp8_f32 v132, v133, v138 op_sel:[0,0,1]
	v_mul_f32_e32 v138, v149, v117
	v_mov_b32_e32 v133, v199
	v_cvt_pk_fp8_f32 v133, v138, v139
	v_mul_f32_e32 v138, v149, v125
	v_mul_f32_e32 v139, v149, v129
	v_cvt_pk_fp8_f32 v133, v138, v139 op_sel:[0,0,1]
	v_add_u32_e32 v139, s48, v137
	ds_write_b128 v144, v[130:133] offset:60928
	s_waitcnt lgkmcnt(0)
	s_barrier
	ds_read_b128 v[130:133], v145 offset:34816
	s_cbranch_scc1 .LBB0_1688
	s_cmp_gt_i32 s58, 2
	s_cbranch_scc0 .LBB0_1689
	s_cmp_eq_u32 s58, 3
	s_mov_b64 s[4:5], -1
	s_cbranch_scc0 .LBB0_1687
	v_lshlrev_b32_e32 v138, 2, v139
	v_lshrrev_b32_e32 v150, 1, v139
	v_and_b32_e32 v138, 16, v138
	v_and_b32_e32 v150, 12, v150
	v_and_b32_e32 v151, 0xffffffe3, v139
	v_or3_b32 v138, v138, v151, v150
	s_mov_b64 s[4:5], 0

; __device__ __forceinline__ float w_qscale(float wmax) { return exp2f(floorf(log2f(128.f / fmaxf(wmax, 1e-30f)))); }
; __device__ __forceinline__ bool witem_decode(const Frame& F, int l, int it, WItem& t) {
;     constexpr int I_GU = 4 * 16, I_DN = 4 * 8, N_GU = NE * I_GU, N_DN = NE * I_DN;
;     const float* wmax = (const float*)((const unsigned*)(F.ws + WS_CTL) + CW_WMAX);
;     int r = it, nblk, item;
;     if (r < N_GU) { const int le = l * NE + r / I_GU; t.W = F.in[16] + (size_t)le * D * 2048; t.WT = (unsigned char*)(F.ws + WS_WGU) + (size_t)le * 2048 * D; t.N = 2048; t.map = 1; nblk = 16; item = r % I_GU; t.scale = w_qscale(wmax[l * 2 + 0]); }
;     else if ((r -= N_GU) < N_DN) { const int le = l * NE + r / I_DN; t.W = F.in[18] + (size_t)le * FF * D; t.WT = (unsigned char*)(F.ws + WS_WDN) + (size_t)le * D * FF; t.N = D; t.map = 3; nblk = 8; item = r % I_DN; t.scale = w_qscale(wmax[l * 2 + 1]); }
;     else return false;
;     t.k0 = 256 * (item / nblk); t.n0 = 128 * (item % nblk); return true;
; }
; __device__ __forceinline__ void witem_load(const WItem& t, int wave, int lane, f32x4 (&v)[16]) {
;     const float* wp = t.W + (size_t)(t.k0 + 32 * wave + 16 * (lane >> 5)) * t.N + t.n0 + 4 * (lane & 31);
; #pragma unroll
;     for (int q = 0; q < 16; ++q) v[q] = __builtin_nontemporal_load((const f32x4*)(wp + (size_t)q * t.N));
; }
; __device__ __forceinline__ void fp8_convert_range(const Frame& F, int l, int start, int stride, int limit) {
;     ...
;     while (ha) {
;         const bool hb = it + stride < limit && witem_decode(F, l, it + stride, tb);
;         if (hb) witem_load(tb, F.wave, F.lane, vb);
;         witem_store(F, ta, va, F.lds);
;         if (!hb) break;
;         it += 2 * stride;
;         ha = it < limit && witem_decode(F, l, it, ta);
;         if (ha) witem_load(ta, F.wave, F.lane, va);
;         witem_store(F, tb, vb, F.lds + 34816);
.LBB0_1938:
	s_load_dword s100, s[4:5], 0x0
	s_mov_b32 s7, 0x43000000
	v_lshlrev_b32_e32 v198, 2, v136
	s_movk_i32 s10, 0xc00
	s_waitcnt lgkmcnt(0)
	v_mov_b32_e32 v1, s100
	v_max_f32_e32 v1, v1, v1
	v_max_f32_e32 v1, 0xda24260, v1
	v_div_scale_f32 v2, s[4:5], v1, v1, s7
	v_rcp_f32_e32 v3, v2
	s_mov_b32 s4, 0x800000
	v_fma_f32 v4, -v2, v3, 1.0
	v_fmac_f32_e32 v3, v4, v3
	v_div_scale_f32 v4, vcc, s7, v1, s7
	v_mul_f32_e32 v5, v4, v3
	v_fma_f32 v10, -v2, v5, v4
	v_fmac_f32_e32 v5, v10, v3
	v_fma_f32 v2, -v2, v5, v4
	v_div_fmas_f32 v2, v2, v3, v5
	v_div_fixup_f32 v1, v2, v1, s7
	v_cmp_gt_f32_e32 vcc, s4, v1
	s_and_b64 s[4:5], vcc, exec
	s_cselect_b32 s4, 32, 0
	v_ldexp_f32 v1, v1, s4
	v_log_f32_e32 v1, v1
	v_cndmask_b32_e32 v2, 0, v232, vcc
	s_mov_b32 s4, 0xc2fc0000
	v_cvt_f32_ubyte0_e32 v3, s6
	v_sub_f32_e32 v1, v1, v2
	v_floor_f32_e32 v1, v1
	v_cmp_gt_f32_e32 vcc, s4, v1
	s_and_b64 s[4:5], vcc, exec
	s_cselect_b32 s4, 0xffffffc0, 0
	v_cndmask_b32_e32 v2, 0, v233, vcc
	v_add_f32_e32 v1, v1, v2
	v_exp_f32_e32 v1, v1
	v_rcp_iflag_f32_e32 v4, v3
	v_ldexp_f32 v1, v1, s4
	s_sext_i32_i8 s4, s3
	v_cvt_f32_i32_e32 v2, s4
	s_ashr_i32 s5, s4, 30
	s_or_b32 s7, s5, 1
	v_mul_f32_e32 v4, v2, v4
	v_trunc_f32_e32 v4, v4
	v_fma_f32 v2, -v4, v3, v2
	v_cvt_i32_f32_e32 v4, v4
	v_cmp_ge_f32_e64 s[4:5], |v2|, v3
	s_and_b64 s[4:5], s[4:5], exec
	s_cselect_b32 s4, s7, 0
	v_readfirstlane_b32 s5, v4
	s_add_i32 s4, s5, s4
	s_sext_i32_i8 s5, s4
	s_mul_i32 s4, s4, s6
	s_lshl_b32 s14, s5, 8
	s_sub_i32 s3, s3, s4
	s_sext_i32_i8 s3, s3
	v_add_u32_e32 v2, s14, v143
	s_lshl_b32 s28, s3, 7
	v_mad_i64_i32 v[2:3], s[4:5], s26, v2, 0
	v_lshl_add_u64 v[2:3], v[2:3], 2, s[50:51]
	s_ashr_i32 s29, s28, 31
	v_lshl_add_u64 v[2:3], s[28:29], 2, v[2:3]
	v_lshl_add_u64 v[10:11], v[2:3], 0, v[198:199]
	s_lshl_b32 s34, s26, 2
	v_lshl_add_u64 v[14:15], v[10:11], 0, s[34:35]
	v_lshl_add_u64 v[18:19], v[14:15], 0, s[34:35]
	v_lshl_add_u64 v[22:23], v[18:19], 0, s[34:35]
	v_lshl_add_u64 v[26:27], v[22:23], 0, s[34:35]
	v_lshl_add_u64 v[30:31], v[26:27], 0, s[34:35]
	v_lshl_add_u64 v[34:35], v[30:31], 0, s[34:35]
	v_lshl_add_u64 v[38:39], v[34:35], 0, s[34:35]
	v_lshl_add_u64 v[42:43], v[38:39], 0, s[34:35]
	v_lshl_add_u64 v[46:47], v[42:43], 0, s[34:35]
	v_lshl_add_u64 v[50:51], v[46:47], 0, s[34:35]
	v_lshl_add_u64 v[54:55], v[50:51], 0, s[34:35]
	v_lshl_add_u64 v[58:59], v[54:55], 0, s[34:35]
	v_lshl_add_u64 v[62:63], v[58:59], 0, s[34:35]
	v_lshl_add_u64 v[66:67], v[62:63], 0, s[34:35]
	global_load_dwordx4 v[2:5], v[10:11], off nt
	s_nop 0
	global_load_dwordx4 v[10:13], v[14:15], off nt
	s_nop 0
	global_load_dwordx4 v[14:17], v[18:19], off nt
	s_nop 0
	global_load_dwordx4 v[18:21], v[22:23], off nt
	s_nop 0
	global_load_dwordx4 v[22:25], v[26:27], off nt
	s_nop 0
	global_load_dwordx4 v[26:29], v[30:31], off nt
	s_nop 0
	global_load_dwordx4 v[30:33], v[34:35], off nt
	s_nop 0
	global_load_dwordx4 v[34:37], v[38:39], off nt
	s_nop 0
	global_load_dwordx4 v[38:41], v[42:43], off nt
	s_nop 0
	global_load_dwordx4 v[42:45], v[46:47], off nt
	s_nop 0
	global_load_dwordx4 v[46:49], v[50:51], off nt
	s_nop 0
	global_load_dwordx4 v[50:53], v[54:55], off nt
	s_nop 0
	global_load_dwordx4 v[54:57], v[58:59], off nt
	s_nop 0
	global_load_dwordx4 v[58:61], v[62:63], off nt
	s_nop 0
	global_load_dwordx4 v[62:65], v[66:67], off nt
	v_lshl_add_u64 v[66:67], v[66:67], 0, s[34:35]
	global_load_dwordx4 v[66:69], v[66:67], off nt
	s_waitcnt vmcnt(16)
	s_branch .Lcvw_5
.LBB0_1939:
	s_waitcnt vmcnt(0)
; #define LAS __attribute__((address_space(3)))
; __device__ __forceinline__ int map_row_rt(int map, int n) { return map == 0 ? n : (map == 1 ? map_row<1>(n) : (map == 3 ? map_row<3>(n) : map_row<2>(n))); }
; __device__ __forceinline__ void witem_store(const Frame& F, const WItem& t, const f32x4 (&v)[16], LAS unsigned char* tile) {
;     const int i = F.lane & 31, hi = F.lane >> 5;
; #pragma unroll
;     for (int j = 0; j < 4; ++j) {
;         u32x4 o;
; #pragma unroll
;         for (int d = 0; d < 4; ++d) { int r = __builtin_amdgcn_cvt_pk_fp8_f32(v[4 * d][j] * t.scale, v[4 * d + 1][j] * t.scale, 0, false);
;             r = __builtin_amdgcn_cvt_pk_fp8_f32(v[4 * d + 2][j] * t.scale, v[4 * d + 3][j] * t.scale, r, true); o[d] = (unsigned)r; }
;         *(LAS u32x4*)(tile + (32 * j + i) * 272 + 32 * F.wave + 16 * hi) = o;
;     }
;     __syncthreads();
;     const int c = F.tid & 15;
; #pragma unroll
;     for (int pass = 0; pass < 4; ++pass) { const int n = (F.tid >> 4) + 32 * pass, rho = (n & 3) * 32 + (n >> 2);
;         const u32x4 o = *(const LAS u32x4*)(tile + rho * 272 + 16 * c);
;         *(u32x4*)(t.WT + (size_t)map_row_rt(t.map, t.n0 + n) * D + t.k0 + 16 * c) = o; }
; }
.Lcvw_5:
	v_mul_f32_e32 v131, v149, v6
	v_mul_f32_e32 v132, v149, v70
	v_mov_b32_e32 v130, v199
	v_cvt_pk_fp8_f32 v130, v131, v132
	v_mul_f32_e32 v131, v149, v74
	v_mul_f32_e32 v132, v149, v78
	v_mul_f32_e32 v133, v149, v86
	v_cvt_pk_fp8_f32 v130, v131, v132 op_sel:[0,0,1]
	v_mul_f32_e32 v132, v149, v82
	v_mov_b32_e32 v131, v199
	v_cvt_pk_fp8_f32 v131, v132, v133
	v_mul_f32_e32 v132, v149, v90
	v_mul_f32_e32 v133, v149, v94
	v_mul_f32_e32 v138, v149, v102
	v_cvt_pk_fp8_f32 v131, v132, v133 op_sel:[0,0,1]
	v_mul_f32_e32 v133, v149, v98
	v_mov_b32_e32 v132, v199
	v_cvt_pk_fp8_f32 v132, v133, v138
	v_mul_f32_e32 v133, v149, v106
	v_mul_f32_e32 v138, v149, v110
	v_mul_f32_e32 v139, v149, v118
	v_cvt_pk_fp8_f32 v132, v133, v138 op_sel:[0,0,1]
	v_mul_f32_e32 v138, v149, v114
	v_mov_b32_e32 v133, v199
	v_cvt_pk_fp8_f32 v133, v138, v139
	v_mul_f32_e32 v138, v149, v122
	v_mul_f32_e32 v139, v149, v126
	s_cmp_lt_i32 s55, 1
	v_cvt_pk_fp8_f32 v133, v138, v139 op_sel:[0,0,1]
	v_mul_f32_e32 v138, v149, v103
	v_mul_f32_e32 v139, v149, v119
	ds_write_b128 v144, v[130:133] offset:34816
	v_mul_f32_e32 v131, v149, v7
	v_mul_f32_e32 v132, v149, v71
	v_mov_b32_e32 v130, v199
	v_cvt_pk_fp8_f32 v130, v131, v132
	v_mul_f32_e32 v131, v149, v75
	v_mul_f32_e32 v132, v149, v79
	v_mul_f32_e32 v133, v149, v87
	v_cvt_pk_fp8_f32 v130, v131, v132 op_sel:[0,0,1]
	v_mul_f32_e32 v132, v149, v83
	v_mov_b32_e32 v131, v199
	v_cvt_pk_fp8_f32 v131, v132, v133
	v_mul_f32_e32 v132, v149, v91
	v_mul_f32_e32 v133, v149, v95
	v_cvt_pk_fp8_f32 v131, v132, v133 op_sel:[0,0,1]
	v_mul_f32_e32 v133, v149, v99
	v_mov_b32_e32 v132, v199
	v_cvt_pk_fp8_f32 v132, v133, v138
	v_mul_f32_e32 v133, v149, v107
	v_mul_f32_e32 v138, v149, v111
	v_cvt_pk_fp8_f32 v132, v133, v138 op_sel:[0,0,1]
	v_mul_f32_e32 v138, v149, v115
	v_mov_b32_e32 v133, v199
	v_cvt_pk_fp8_f32 v133, v138, v139
	v_mul_f32_e32 v138, v149, v123
	v_mul_f32_e32 v139, v149, v127
	v_cvt_pk_fp8_f32 v133, v138, v139 op_sel:[0,0,1]
	v_mul_f32_e32 v138, v149, v104
	v_mul_f32_e32 v139, v149, v120
	ds_write_b128 v144, v[130:133] offset:43520
	v_mul_f32_e32 v131, v149, v8
	v_mul_f32_e32 v132, v149, v72
	v_mov_b32_e32 v130, v199
	v_cvt_pk_fp8_f32 v130, v131, v132
	v_mul_f32_e32 v131, v149, v76
	v_mul_f32_e32 v132, v149, v80
	v_mul_f32_e32 v133, v149, v88
	v_cvt_pk_fp8_f32 v130, v131, v132 op_sel:[0,0,1]
	v_mul_f32_e32 v132, v149, v84
	v_mov_b32_e32 v131, v199
	v_cvt_pk_fp8_f32 v131, v132, v133
	v_mul_f32_e32 v132, v149, v92
	v_mul_f32_e32 v133, v149, v96
	v_cvt_pk_fp8_f32 v131, v132, v133 op_sel:[0,0,1]
	v_mul_f32_e32 v133, v149, v100
	v_mov_b32_e32 v132, v199
	v_cvt_pk_fp8_f32 v132, v133, v138
	v_mul_f32_e32 v133, v149, v108
	v_mul_f32_e32 v138, v149, v112
	v_cvt_pk_fp8_f32 v132, v133, v138 op_sel:[0,0,1]
	v_mul_f32_e32 v138, v149, v116
	v_mov_b32_e32 v133, v199
	v_cvt_pk_fp8_f32 v133, v138, v139
	v_mul_f32_e32 v138, v149, v124
	v_mul_f32_e32 v139, v149, v128
	v_cvt_pk_fp8_f32 v133, v138, v139 op_sel:[0,0,1]
	v_mul_f32_e32 v138, v149, v105
	v_mul_f32_e32 v139, v149, v121
	ds_write_b128 v144, v[130:133] offset:52224
	v_mul_f32_e32 v131, v149, v9
	v_mul_f32_e32 v132, v149, v73
	v_mov_b32_e32 v130, v199
	v_cvt_pk_fp8_f32 v130, v131, v132
	v_mul_f32_e32 v131, v149, v77
	v_mul_f32_e32 v132, v149, v81
	v_mul_f32_e32 v133, v149, v89
	v_cvt_pk_fp8_f32 v130, v131, v132 op_sel:[0,0,1]
	v_mul_f32_e32 v132, v149, v85
	v_mov_b32_e32 v131, v199
	v_cvt_pk_fp8_f32 v131, v132, v133
	v_mul_f32_e32 v132, v149, v93
	v_mul_f32_e32 v133, v149, v97
	v_cvt_pk_fp8_f32 v131, v132, v133 op_sel:[0,0,1]
	v_mul_f32_e32 v133, v149, v101
	v_mov_b32_e32 v132, v199
	v_cvt_pk_fp8_f32 v132, v133, v138
	v_mul_f32_e32 v133, v149, v109
	v_mul_f32_e32 v138, v149, v113
	v_cvt_pk_fp8_f32 v132, v133, v138 op_sel:[0,0,1]
	v_mul_f32_e32 v138, v149, v117
	v_mov_b32_e32 v133, v199
	v_cvt_pk_fp8_f32 v133, v138, v139
	v_mul_f32_e32 v138, v149, v125
	v_mul_f32_e32 v139, v149, v129
	v_cvt_pk_fp8_f32 v133, v138, v139 op_sel:[0,0,1]
	v_add_u32_e32 v139, s46, v137
	ds_write_b128 v144, v[130:133] offset:60928
	s_waitcnt lgkmcnt(0)
	s_barrier
	ds_read_b128 v[130:133], v145 offset:34816
	s_cbranch_scc1 .LBB0_1944
	s_cmp_gt_i32 s55, 2
	s_cbranch_scc0 .LBB0_1945
	s_cmp_eq_u32 s55, 3
	s_mov_b64 s[4:5], -1
	s_cbranch_scc0 .LBB0_1943
	v_lshlrev_b32_e32 v138, 2, v139
	v_lshrrev_b32_e32 v150, 1, v139
	v_and_b32_e32 v138, 16, v138
	v_and_b32_e32 v150, 12, v150
	v_and_b32_e32 v151, 0xffffffe3, v139
	v_or3_b32 v138, v138, v151, v150
	s_mov_b64 s[4:5], 0
